# adds 64-bit zeroing of the GEMM accumulators (half the move instructions per tile)
# baseline (speedup 1.0000x reference)
.LBB0_190:
	s_ashr_i32 s15, s14, 31
	s_lshl_b64 s[8:9], s[14:15], 19
	v_readlane_b32 s18, v254, 49
	v_readlane_b32 s19, v254, 50
	s_add_u32 s18, s18, s8
	s_addc_u32 s19, s19, s9
	s_and_b64 s[8:9], s[2:3], exec
	s_cselect_b32 s15, s19, s5
	s_cselect_b32 s23, s18, s4
	s_ashr_i32 s17, s16, 31
	s_lshl_b64 s[8:9], s[16:17], 19
	s_add_u32 s20, s26, s8
	s_addc_u32 s21, s27, s9
	s_and_b64 s[8:9], s[2:3], exec
	s_cselect_b32 s17, s21, s7
	s_cselect_b32 s24, s20, s6
	s_add_u32 s4, s4, 0x40080
	s_addc_u32 s5, s5, 0
	s_add_u32 s25, s6, 0x100
	v_mov_b32_e32 v0, 0
	s_addc_u32 s35, s7, 0
	s_mov_b32 s51, -2
	v_mov_b32_e32 v1, 0
	v_mov_b64_e32 v[2:3], 0
	v_mov_b64_e32 v[4:5], 0
	v_mov_b64_e32 v[6:7], 0
	v_mov_b64_e32 v[8:9], 0
	v_mov_b64_e32 v[10:11], 0
	v_mov_b64_e32 v[12:13], 0
	v_mov_b64_e32 v[14:15], 0
	v_mov_b64_e32 v[16:17], 0
	v_mov_b64_e32 v[18:19], 0
	v_mov_b64_e32 v[20:21], 0
	v_mov_b64_e32 v[22:23], 0
	v_mov_b64_e32 v[24:25], 0
	v_mov_b64_e32 v[26:27], 0
	v_mov_b64_e32 v[28:29], 0
	v_mov_b64_e32 v[30:31], 0
	v_mov_b64_e32 v[32:33], 0
	v_mov_b64_e32 v[34:35], 0
	v_mov_b64_e32 v[36:37], 0
	v_mov_b64_e32 v[38:39], 0
	v_mov_b64_e32 v[40:41], 0
	v_mov_b64_e32 v[42:43], 0
	v_mov_b64_e32 v[44:45], 0
	v_mov_b64_e32 v[46:47], 0
	v_mov_b64_e32 v[48:49], 0
	v_mov_b64_e32 v[50:51], 0
	v_mov_b64_e32 v[52:53], 0
	v_mov_b64_e32 v[54:55], 0
	v_mov_b64_e32 v[56:57], 0
	v_mov_b64_e32 v[58:59], 0
	v_mov_b64_e32 v[60:61], 0
	v_mov_b64_e32 v[62:63], 0
	v_mov_b64_e32 v[64:65], 0
	v_mov_b64_e32 v[66:67], 0
	v_mov_b64_e32 v[68:69], 0
	v_mov_b64_e32 v[70:71], 0
	v_mov_b64_e32 v[72:73], 0
	v_mov_b64_e32 v[74:75], 0
	v_mov_b64_e32 v[76:77], 0
	v_mov_b64_e32 v[78:79], 0
	v_mov_b64_e32 v[80:81], 0
	v_mov_b64_e32 v[82:83], 0
	v_mov_b64_e32 v[84:85], 0
	v_mov_b64_e32 v[86:87], 0
	v_mov_b64_e32 v[88:89], 0
	v_mov_b64_e32 v[90:91], 0
	v_mov_b64_e32 v[92:93], 0
	v_mov_b64_e32 v[94:95], 0
	v_mov_b64_e32 v[96:97], 0
	v_mov_b64_e32 v[98:99], 0
	v_mov_b64_e32 v[100:101], 0
	v_mov_b64_e32 v[102:103], 0
	v_mov_b64_e32 v[120:121], 0
	v_mov_b64_e32 v[122:123], 0
	v_mov_b64_e32 v[124:125], 0
	v_mov_b64_e32 v[126:127], 0
	v_mov_b64_e32 v[128:129], 0
	v_mov_b64_e32 v[130:131], 0
	v_mov_b64_e32 v[132:133], 0
	v_mov_b64_e32 v[134:135], 0
	v_mov_b64_e32 v[136:137], 0
	v_mov_b64_e32 v[138:139], 0
	v_mov_b64_e32 v[140:141], 0
	v_mov_b64_e32 v[142:143], 0

.LBB0_472:
	s_ashr_i32 s15, s14, 31
	s_lshl_b64 s[8:9], s[14:15], 19
	v_readlane_b32 s18, v254, 49
	v_readlane_b32 s19, v254, 50
	s_add_u32 s18, s18, s8
	s_addc_u32 s19, s19, s9
	s_and_b64 s[8:9], s[2:3], exec
	s_cselect_b32 s15, s19, s5
	s_cselect_b32 s23, s18, s4
	s_ashr_i32 s17, s16, 31
	s_lshl_b64 s[8:9], s[16:17], 19
	s_add_u32 s20, s26, s8
	s_addc_u32 s21, s27, s9
	s_and_b64 s[8:9], s[2:3], exec
	s_cselect_b32 s17, s21, s7
	s_cselect_b32 s41, s20, s6
	s_add_u32 s4, s4, 0x40080
	s_addc_u32 s5, s5, 0
	s_add_u32 s46, s6, 0x100
	v_mov_b32_e32 v4, 0
	s_addc_u32 s47, s7, 0
	s_mov_b32 s50, -2
	v_mov_b64_e32 v[0:1], 0
	v_mov_b64_e32 v[2:3], 0
	v_mov_b32_e32 v5, 0
	v_mov_b64_e32 v[6:7], 0
	v_mov_b64_e32 v[8:9], 0
	v_mov_b64_e32 v[10:11], 0
	v_mov_b64_e32 v[12:13], 0
	v_mov_b64_e32 v[14:15], 0
	v_mov_b64_e32 v[16:17], 0
	v_mov_b64_e32 v[18:19], 0
	v_mov_b64_e32 v[20:21], 0
	v_mov_b64_e32 v[22:23], 0
	v_mov_b64_e32 v[24:25], 0
	v_mov_b64_e32 v[26:27], 0
	v_mov_b64_e32 v[28:29], 0
	v_mov_b64_e32 v[30:31], 0
	v_mov_b64_e32 v[32:33], 0
	v_mov_b64_e32 v[34:35], 0
	v_mov_b64_e32 v[36:37], 0
	v_mov_b64_e32 v[38:39], 0
	v_mov_b64_e32 v[40:41], 0
	v_mov_b64_e32 v[42:43], 0
	v_mov_b64_e32 v[44:45], 0
	v_mov_b64_e32 v[46:47], 0
	v_mov_b64_e32 v[48:49], 0
	v_mov_b64_e32 v[50:51], 0
	v_mov_b64_e32 v[52:53], 0
	v_mov_b64_e32 v[54:55], 0
	v_mov_b64_e32 v[56:57], 0
	v_mov_b64_e32 v[58:59], 0
	v_mov_b64_e32 v[60:61], 0
	v_mov_b64_e32 v[62:63], 0
	v_mov_b64_e32 v[64:65], 0
	v_mov_b64_e32 v[66:67], 0
	v_mov_b64_e32 v[68:69], 0
	v_mov_b64_e32 v[70:71], 0
	v_mov_b64_e32 v[72:73], 0
	v_mov_b64_e32 v[74:75], 0
	v_mov_b64_e32 v[76:77], 0
	v_mov_b64_e32 v[78:79], 0
	v_mov_b64_e32 v[80:81], 0
	v_mov_b64_e32 v[82:83], 0
	v_mov_b64_e32 v[84:85], 0
	v_mov_b64_e32 v[86:87], 0
	v_mov_b64_e32 v[88:89], 0
	v_mov_b64_e32 v[90:91], 0
	v_mov_b64_e32 v[92:93], 0
	v_mov_b64_e32 v[94:95], 0
	v_mov_b64_e32 v[96:97], 0
	v_mov_b64_e32 v[98:99], 0
	v_mov_b64_e32 v[100:101], 0
	v_mov_b64_e32 v[102:103], 0
	v_mov_b64_e32 v[104:105], 0
	v_mov_b64_e32 v[106:107], 0
	v_mov_b64_e32 v[108:109], 0
	v_mov_b64_e32 v[110:111], 0
	v_mov_b64_e32 v[112:113], 0
	v_mov_b64_e32 v[114:115], 0
	v_mov_b64_e32 v[116:117], 0
	v_mov_b64_e32 v[118:119], 0
	v_mov_b64_e32 v[120:121], 0
	v_mov_b64_e32 v[122:123], 0
	v_mov_b64_e32 v[124:125], 0
	v_mov_b64_e32 v[126:127], 0

.LBB0_1051:
	s_ashr_i32 s17, s16, 31
	s_lshl_b64 s[0:1], s[16:17], 19
	v_readlane_b32 s15, v255, 3
	s_add_u32 s18, s15, s0
	v_readlane_b32 s0, v255, 4
	s_addc_u32 s19, s0, s1
	s_and_b64 s[0:1], s[4:5], exec
	s_cselect_b32 s17, s19, s25
	s_cselect_b32 vcc_lo, s18, s24
	s_ashr_i32 s15, s14, 31
	s_lshl_b64 s[0:1], s[14:15], 19
	s_add_u32 s20, s28, s0
	s_addc_u32 s21, s29, s1
	s_and_b64 s[0:1], s[4:5], exec
	s_cselect_b32 s15, s21, s23
	s_cselect_b32 vcc_hi, s20, s22
	s_add_u32 s0, s24, 0x40080
	s_addc_u32 s1, s25, 0
	s_add_u32 s84, s22, 0x100
	v_mov_b32_e32 v0, 0
	s_addc_u32 s85, s23, 0
	s_mov_b32 s64, -2
	v_mov_b32_e32 v1, 0
	v_mov_b64_e32 v[2:3], 0
	v_mov_b64_e32 v[4:5], 0
	v_mov_b64_e32 v[6:7], 0
	v_mov_b64_e32 v[8:9], 0
	v_mov_b64_e32 v[10:11], 0
	v_mov_b64_e32 v[12:13], 0
	v_mov_b64_e32 v[14:15], 0
	v_mov_b64_e32 v[16:17], 0
	v_mov_b64_e32 v[18:19], 0
	v_mov_b64_e32 v[20:21], 0
	v_mov_b64_e32 v[22:23], 0
	v_mov_b64_e32 v[24:25], 0
	v_mov_b64_e32 v[26:27], 0
	v_mov_b64_e32 v[28:29], 0
	v_mov_b64_e32 v[30:31], 0
	v_mov_b64_e32 v[32:33], 0
	v_mov_b64_e32 v[34:35], 0
	v_mov_b64_e32 v[36:37], 0
	v_mov_b64_e32 v[38:39], 0
	v_mov_b64_e32 v[40:41], 0
	v_mov_b64_e32 v[42:43], 0
	v_mov_b64_e32 v[44:45], 0
	v_mov_b64_e32 v[46:47], 0
	v_mov_b64_e32 v[48:49], 0
	v_mov_b64_e32 v[50:51], 0
	v_mov_b64_e32 v[52:53], 0
	v_mov_b64_e32 v[54:55], 0
	v_mov_b64_e32 v[56:57], 0
	v_mov_b64_e32 v[58:59], 0
	v_mov_b64_e32 v[60:61], 0
	v_mov_b64_e32 v[62:63], 0
	v_mov_b64_e32 v[76:77], 0
	v_mov_b64_e32 v[78:79], 0
	v_mov_b64_e32 v[84:85], 0
	v_mov_b64_e32 v[86:87], 0
	v_mov_b64_e32 v[88:89], 0
	v_mov_b64_e32 v[90:91], 0
	v_mov_b64_e32 v[92:93], 0
	v_mov_b64_e32 v[94:95], 0
	v_mov_b64_e32 v[96:97], 0
	v_mov_b64_e32 v[98:99], 0
	v_mov_b64_e32 v[100:101], 0
	v_mov_b64_e32 v[102:103], 0
	v_mov_b64_e32 v[104:105], 0
	v_mov_b64_e32 v[106:107], 0
	v_mov_b64_e32 v[108:109], 0
	v_mov_b64_e32 v[110:111], 0
	v_mov_b64_e32 v[112:113], 0
	v_mov_b64_e32 v[114:115], 0
	v_mov_b64_e32 v[116:117], 0
	v_mov_b64_e32 v[118:119], 0
	v_mov_b64_e32 v[120:121], 0
	v_mov_b64_e32 v[122:123], 0
	v_mov_b64_e32 v[124:125], 0
	v_mov_b64_e32 v[126:127], 0
	v_mov_b64_e32 v[128:129], 0
	v_mov_b64_e32 v[130:131], 0
	v_mov_b64_e32 v[132:133], 0
	v_mov_b64_e32 v[134:135], 0
	v_mov_b64_e32 v[136:137], 0
	v_mov_b64_e32 v[138:139], 0
	v_mov_b64_e32 v[140:141], 0
	v_mov_b64_e32 v[142:143], 0

.LBB0_1175:
	s_ashr_i32 s13, s12, 31
	s_lshl_b64 s[14:15], s[12:13], 19
	v_readlane_b32 s16, v254, 49
	v_readlane_b32 s17, v254, 50
	s_add_u32 s14, s16, s14
	s_addc_u32 s15, s17, s15
	s_and_b64 s[16:17], s[2:3], exec
	s_cselect_b32 s13, s15, s19
	s_cselect_b32 s94, s14, s18
	s_ashr_i32 s11, s10, 31
	s_lshl_b64 s[16:17], s[10:11], 19
	s_add_u32 s16, s24, s16
	s_addc_u32 s17, s25, s17
	s_and_b64 s[22:23], s[2:3], exec
	s_cselect_b32 s11, s17, s21
	s_cselect_b32 s95, s16, s20
	s_add_u32 s18, s18, 0x40080
	s_addc_u32 s19, s19, 0
	s_add_u32 s84, s20, 0x100
	v_mov_b32_e32 v0, 0
	s_addc_u32 s85, s21, 0
	s_mov_b32 s64, -2
	v_mov_b32_e32 v1, 0
	v_mov_b64_e32 v[2:3], 0
	v_mov_b64_e32 v[4:5], 0
	v_mov_b64_e32 v[6:7], 0
	v_mov_b64_e32 v[8:9], 0
	v_mov_b64_e32 v[10:11], 0
	v_mov_b64_e32 v[12:13], 0
	v_mov_b64_e32 v[14:15], 0
	v_mov_b64_e32 v[16:17], 0
	v_mov_b64_e32 v[18:19], 0
	v_mov_b64_e32 v[20:21], 0
	v_mov_b64_e32 v[22:23], 0
	v_mov_b64_e32 v[24:25], 0
	v_mov_b64_e32 v[26:27], 0
	v_mov_b64_e32 v[28:29], 0
	v_mov_b64_e32 v[30:31], 0
	v_mov_b64_e32 v[32:33], 0
	v_mov_b64_e32 v[34:35], 0
	v_mov_b64_e32 v[36:37], 0
	v_mov_b64_e32 v[38:39], 0
	v_mov_b64_e32 v[40:41], 0
	v_mov_b64_e32 v[42:43], 0
	v_mov_b64_e32 v[44:45], 0
	v_mov_b64_e32 v[46:47], 0
	v_mov_b64_e32 v[48:49], 0
	v_mov_b64_e32 v[50:51], 0
	v_mov_b64_e32 v[52:53], 0
	v_mov_b64_e32 v[54:55], 0
	v_mov_b64_e32 v[56:57], 0
	v_mov_b64_e32 v[58:59], 0
	v_mov_b64_e32 v[60:61], 0
	v_mov_b64_e32 v[62:63], 0
	v_mov_b64_e32 v[64:65], 0
	v_mov_b64_e32 v[66:67], 0
	v_mov_b64_e32 v[68:69], 0
	v_mov_b64_e32 v[70:71], 0
	v_mov_b64_e32 v[88:89], 0
	v_mov_b64_e32 v[90:91], 0
	v_mov_b64_e32 v[92:93], 0
	v_mov_b64_e32 v[94:95], 0
	v_mov_b64_e32 v[96:97], 0
	v_mov_b64_e32 v[98:99], 0
	v_mov_b64_e32 v[100:101], 0
	v_mov_b64_e32 v[102:103], 0
	v_mov_b64_e32 v[104:105], 0
	v_mov_b64_e32 v[106:107], 0
	v_mov_b64_e32 v[108:109], 0
	v_mov_b64_e32 v[110:111], 0
	v_mov_b64_e32 v[112:113], 0
	v_mov_b64_e32 v[114:115], 0
	v_mov_b64_e32 v[116:117], 0
	v_mov_b64_e32 v[118:119], 0
	v_mov_b64_e32 v[120:121], 0
	v_mov_b64_e32 v[122:123], 0
	v_mov_b64_e32 v[124:125], 0
	v_mov_b64_e32 v[126:127], 0
	v_mov_b64_e32 v[128:129], 0
	v_mov_b64_e32 v[130:131], 0
	v_mov_b64_e32 v[132:133], 0
	v_mov_b64_e32 v[134:135], 0
	v_mov_b64_e32 v[136:137], 0
	v_mov_b64_e32 v[138:139], 0
	v_mov_b64_e32 v[140:141], 0
	v_mov_b64_e32 v[142:143], 0

.LBB0_1236:
	s_ashr_i32 s13, s12, 31
	s_lshl_b64 s[16:17], s[12:13], 21
	s_add_u32 s11, s70, s16
	s_addc_u32 s13, s71, s17
	s_lshl_b64 s[16:17], s[48:49], 11
	s_cmp_gt_i32 s48, -1
	s_cselect_b32 s53, s16, 0
	s_cselect_b32 s25, s17, 0
	s_add_u32 s16, s11, s53
	s_addc_u32 s17, s13, s25
	s_and_b64 s[18:19], s[14:15], exec
	s_cselect_b32 s13, s17, s21
	s_cselect_b32 s35, s16, s20
	s_ashr_i32 s11, s10, 31
	s_lshl_b64 s[18:19], s[10:11], 21
	s_add_u32 s11, s26, s18
	s_addc_u32 s19, s27, s19
	s_add_u32 s18, s11, s53
	s_addc_u32 s19, s19, s25
	s_and_b64 s[64:65], s[14:15], exec
	s_cselect_b32 s11, s19, s23
	s_cselect_b32 s53, s18, s22
	s_cmp_lt_i32 s51, 0
	s_cselect_b32 s55, 64, 16
	s_add_i32 s56, s55, -2
	s_add_u32 s20, s20, 0x100080
	s_addc_u32 s21, s21, 0
	s_add_u32 s84, s22, 0x100
	v_mov_b32_e32 v0, 0
	s_mov_b32 s24, 0
	s_addc_u32 s85, s23, 0
	v_mov_b32_e32 v1, 0
	v_mov_b64_e32 v[2:3], 0
	v_mov_b64_e32 v[4:5], 0
	v_mov_b64_e32 v[6:7], 0
	v_mov_b64_e32 v[8:9], 0
	v_mov_b64_e32 v[10:11], 0
	v_mov_b64_e32 v[12:13], 0
	v_mov_b64_e32 v[14:15], 0
	v_mov_b64_e32 v[16:17], 0
	v_mov_b64_e32 v[18:19], 0
	v_mov_b64_e32 v[20:21], 0
	v_mov_b64_e32 v[22:23], 0
	v_mov_b64_e32 v[24:25], 0
	v_mov_b64_e32 v[26:27], 0
	v_mov_b64_e32 v[28:29], 0
	v_mov_b64_e32 v[30:31], 0
	v_mov_b64_e32 v[32:33], 0
	v_mov_b64_e32 v[34:35], 0
	v_mov_b64_e32 v[36:37], 0
	v_mov_b64_e32 v[38:39], 0
	v_mov_b64_e32 v[40:41], 0
	v_mov_b64_e32 v[42:43], 0
	v_mov_b64_e32 v[44:45], 0
	v_mov_b64_e32 v[46:47], 0
	v_mov_b64_e32 v[48:49], 0
	v_mov_b64_e32 v[50:51], 0
	v_mov_b64_e32 v[52:53], 0
	v_mov_b64_e32 v[54:55], 0
	v_mov_b64_e32 v[56:57], 0
	v_mov_b64_e32 v[58:59], 0
	v_mov_b64_e32 v[60:61], 0
	v_mov_b64_e32 v[62:63], 0
	v_mov_b64_e32 v[64:65], 0
	v_mov_b64_e32 v[66:67], 0
	v_mov_b64_e32 v[68:69], 0
	v_mov_b64_e32 v[70:71], 0
	v_mov_b64_e32 v[72:73], 0
	v_mov_b64_e32 v[74:75], 0
	v_mov_b64_e32 v[76:77], 0
	v_mov_b64_e32 v[78:79], 0
	v_mov_b64_e32 v[80:81], 0
	v_mov_b64_e32 v[82:83], 0
	v_mov_b64_e32 v[84:85], 0
	v_mov_b64_e32 v[86:87], 0
	v_mov_b64_e32 v[88:89], 0
	v_mov_b64_e32 v[90:91], 0
	v_mov_b64_e32 v[92:93], 0
	v_mov_b64_e32 v[94:95], 0
	v_mov_b64_e32 v[96:97], 0
	v_mov_b64_e32 v[98:99], 0
	v_mov_b64_e32 v[100:101], 0
	v_mov_b64_e32 v[102:103], 0
	v_mov_b64_e32 v[104:105], 0
	v_mov_b64_e32 v[106:107], 0
	v_mov_b64_e32 v[108:109], 0
	v_mov_b64_e32 v[110:111], 0
	v_mov_b64_e32 v[112:113], 0
	v_mov_b64_e32 v[114:115], 0
	v_mov_b64_e32 v[116:117], 0
	v_mov_b64_e32 v[118:119], 0
	v_mov_b64_e32 v[120:121], 0
	v_mov_b64_e32 v[122:123], 0
	v_mov_b64_e32 v[124:125], 0
	v_mov_b64_e32 v[126:127], 0

.LBB0_1361:
	s_mov_b64 s[8:9], s[4:5]
	s_and_b64 s[4:5], s[6:7], exec
	s_cselect_b32 s4, s10, s10
	s_ashr_i32 s5, s4, 31
	s_lshl_b64 s[4:5], s[4:5], 21
	s_add_u32 s4, s70, s4
	s_addc_u32 s5, s71, s5
	v_writelane_b32 v254, s10, 43
	s_and_b64 s[10:11], s[6:7], exec
	v_readlane_b32 s10, v254, 61
	v_readlane_b32 s11, v254, 62
	s_cselect_b32 s22, s5, s9
	s_cselect_b32 s23, s4, s8
	s_cselect_b32 s24, s11, s11
	s_cselect_b32 s25, s10, s10
	s_add_u32 s8, s8, 0x100080
	s_addc_u32 s9, s9, 0
	s_add_u32 s26, s10, 0x100
	v_mov_b32_e32 v0, 0
	s_addc_u32 s27, s11, 0
	s_mov_b32 s28, -2
	v_mov_b32_e32 v1, 0
	v_mov_b64_e32 v[2:3], 0
	v_mov_b64_e32 v[4:5], 0
	v_mov_b64_e32 v[6:7], 0
	v_mov_b64_e32 v[8:9], 0
	v_mov_b64_e32 v[10:11], 0
	v_mov_b64_e32 v[12:13], 0
	v_mov_b64_e32 v[14:15], 0
	v_mov_b64_e32 v[16:17], 0
	v_mov_b64_e32 v[18:19], 0
	v_mov_b64_e32 v[20:21], 0
	v_mov_b64_e32 v[22:23], 0
	v_mov_b64_e32 v[24:25], 0
	v_mov_b64_e32 v[26:27], 0
	v_mov_b64_e32 v[28:29], 0
	v_mov_b64_e32 v[30:31], 0
	v_mov_b64_e32 v[40:41], 0
	v_mov_b64_e32 v[42:43], 0
	v_mov_b64_e32 v[44:45], 0
	v_mov_b64_e32 v[46:47], 0
	v_mov_b64_e32 v[48:49], 0
	v_mov_b64_e32 v[50:51], 0
	v_mov_b64_e32 v[52:53], 0
	v_mov_b64_e32 v[54:55], 0
	v_mov_b64_e32 v[56:57], 0
	v_mov_b64_e32 v[58:59], 0
	v_mov_b64_e32 v[60:61], 0
	v_mov_b64_e32 v[62:63], 0
	v_mov_b64_e32 v[64:65], 0
	v_mov_b64_e32 v[66:67], 0
	v_mov_b64_e32 v[68:69], 0
	v_mov_b64_e32 v[70:71], 0
	v_mov_b64_e32 v[80:81], 0
	v_mov_b64_e32 v[82:83], 0
	v_mov_b64_e32 v[84:85], 0
	v_mov_b64_e32 v[86:87], 0
	v_mov_b64_e32 v[88:89], 0
	v_mov_b64_e32 v[90:91], 0
	v_mov_b64_e32 v[92:93], 0
	v_mov_b64_e32 v[94:95], 0
	v_mov_b64_e32 v[96:97], 0
	v_mov_b64_e32 v[98:99], 0
	v_mov_b64_e32 v[100:101], 0
	v_mov_b64_e32 v[102:103], 0
	v_mov_b64_e32 v[104:105], 0
	v_mov_b64_e32 v[106:107], 0
	v_mov_b64_e32 v[108:109], 0
	v_mov_b64_e32 v[110:111], 0
	v_mov_b64_e32 v[112:113], 0
	v_mov_b64_e32 v[114:115], 0
	v_mov_b64_e32 v[116:117], 0
	v_mov_b64_e32 v[118:119], 0
	v_mov_b64_e32 v[120:121], 0
	v_mov_b64_e32 v[122:123], 0
	v_mov_b64_e32 v[124:125], 0
	v_mov_b64_e32 v[126:127], 0
	v_mov_b64_e32 v[128:129], 0
	v_mov_b64_e32 v[130:131], 0
	v_mov_b64_e32 v[132:133], 0
	v_mov_b64_e32 v[134:135], 0
	v_mov_b64_e32 v[136:137], 0
	v_mov_b64_e32 v[138:139], 0
	v_mov_b64_e32 v[140:141], 0
	v_mov_b64_e32 v[142:143], 0
